# placement: inter-chunk scan body moved 4 bytes (start at 40 mod 64), P8 and PEER placements kept
# speedup vs baseline: 1.0067x; 1.0005x over previous
; __device__ __forceinline__ float bf2f(bf16 v) { return __uint_as_float(((unsigned)v) << 16); }
; __device__ __forceinline__ unsigned f2bfu(float f) { return (unsigned)__builtin_bit_cast(unsigned short, (__bf16)f); }
; __global__ void __launch_bounds__(NTHR, 2) k_main(Args a) {
;     ...
;         for (int idx = gtid; idx < 2 * 8 * 8192; idx += gthreads) {
;             const int pn = idx & 8191, h = (idx >> 13) & 7, b = idx >> 16;
;             float run = 0.f;
; #pragma unroll 1
;             for (int c0 = 0; c0 < 64; c0 += 8) {
;                 float st[8], dc[8];
; #pragma unroll
;                 for (int j = 0; j < 8; ++j) { const int bch = (b * 64 + c0 + j) * 8 + h; st[j] = bf2f(__builtin_nontemporal_load(&STATES[(size_t)bch * 8192 + pn])); dc[j] = CDEC[bch]; }
; #pragma unroll
;                 for (int j = 0; j < 8; ++j) { const int bch = (b * 64 + c0 + j) * 8 + h; __builtin_amdgcn_raw_buffer_store_b16((short)f2bfu(run), rsPV, (int)(((unsigned)bch * 8192u + (unsigned)pn) * 2u), 0, 16); run = dc[j] * run + st[j]; }
;             }
;         }
.LBB0_377:
	v_and_b32_e32 v2, 0x1fff, v8
	v_ashrrev_i32_e32 v10, 10, v8
	v_lshlrev_b32_e32 v2, 1, v2
	v_lshl_add_u64 v[4:5], s[58:59], 0, v[2:3]
	v_lshrrev_b32_e32 v2, 6, v10
	v_bfe_u32 v6, v8, 13, 3
	v_and_b32_e32 v7, 0x1fffe, v9
	v_lshlrev_b32_e32 v10, 9, v2
	v_lshlrev_b32_e32 v2, 23, v2
	v_or3_b32 v6, v10, v6, 56
	v_or3_b32 v2, v2, v7, s10
	s_mov_b32 s12, -8
	v_mov_b32_e32 v10, 0
	s_nop 0
	v_subrev_u32_e32 v46, 56, v6
	v_and_b32_e32 v47, 0x1fff, v8
	v_lshlrev_b32_e32 v47, 1, v47
	v_lshl_add_u32 v47, v46, 14, v47
	v_lshlrev_b32_e32 v50, 2, v46
	v_add_u32_e32 v51, 0xfff20000, v2
	v_readfirstlane_b32 s44, v50
	s_nop 3
	s_add_u32 s46, s82, s44
	s_addc_u32 s47, s83, 0
	global_load_ushort v128, v47, s[58:59] nt
	v_add_u32_e32 v53, 0x20000, v47
	global_load_ushort v129, v53, s[58:59] nt
	v_add_u32_e32 v53, 0x40000, v47
	global_load_ushort v130, v53, s[58:59] nt
	v_add_u32_e32 v53, 0x60000, v47
	global_load_ushort v131, v53, s[58:59] nt
	v_add_u32_e32 v53, 0x80000, v47
	global_load_ushort v132, v53, s[58:59] nt
	v_add_u32_e32 v53, 0xa0000, v47
	global_load_ushort v133, v53, s[58:59] nt
	v_add_u32_e32 v53, 0xc0000, v47
	global_load_ushort v134, v53, s[58:59] nt
	v_add_u32_e32 v53, 0xe0000, v47
	global_load_ushort v135, v53, s[58:59] nt
	v_add_u32_e32 v53, 0x100000, v47
	global_load_ushort v136, v53, s[58:59] nt
	v_add_u32_e32 v53, 0x120000, v47
	global_load_ushort v137, v53, s[58:59] nt
	v_add_u32_e32 v53, 0x140000, v47
	global_load_ushort v138, v53, s[58:59] nt
	v_add_u32_e32 v53, 0x160000, v47
	global_load_ushort v139, v53, s[58:59] nt
	v_add_u32_e32 v53, 0x180000, v47
	global_load_ushort v140, v53, s[58:59] nt
	v_add_u32_e32 v53, 0x1a0000, v47
	global_load_ushort v141, v53, s[58:59] nt
	v_add_u32_e32 v53, 0x1c0000, v47
	global_load_ushort v142, v53, s[58:59] nt
	v_add_u32_e32 v53, 0x1e0000, v47
	global_load_ushort v143, v53, s[58:59] nt
	s_load_dword s64, s[46:47], 0x0
	s_load_dword s65, s[46:47], 0x20
	s_load_dword s66, s[46:47], 0x40
	s_load_dword s67, s[46:47], 0x60
	s_load_dword s68, s[46:47], 0x80
	s_load_dword s69, s[46:47], 0xa0
	s_load_dword s70, s[46:47], 0xc0
	s_load_dword s71, s[46:47], 0xe0
	s_load_dword s72, s[46:47], 0x100
	s_load_dword s73, s[46:47], 0x120
	s_load_dword s74, s[46:47], 0x140
	s_load_dword s75, s[46:47], 0x160
	s_load_dword s76, s[46:47], 0x180
	s_load_dword s77, s[46:47], 0x1a0
	s_load_dword s78, s[46:47], 0x1c0
	s_load_dword s79, s[46:47], 0x1e0
	v_add_u32_e32 v53, 0x200000, v47
	global_load_ushort v144, v53, s[58:59] nt
	v_add_u32_e32 v53, 0x220000, v47
	global_load_ushort v145, v53, s[58:59] nt
	v_add_u32_e32 v53, 0x240000, v47
	global_load_ushort v146, v53, s[58:59] nt
	v_add_u32_e32 v53, 0x260000, v47
	global_load_ushort v147, v53, s[58:59] nt
	v_add_u32_e32 v53, 0x280000, v47
	global_load_ushort v148, v53, s[58:59] nt
	v_add_u32_e32 v53, 0x2a0000, v47
	global_load_ushort v149, v53, s[58:59] nt
	v_add_u32_e32 v53, 0x2c0000, v47
	global_load_ushort v150, v53, s[58:59] nt
	v_add_u32_e32 v53, 0x2e0000, v47
	global_load_ushort v151, v53, s[58:59] nt
	v_add_u32_e32 v53, 0x300000, v47
	global_load_ushort v152, v53, s[58:59] nt
	v_add_u32_e32 v53, 0x320000, v47
	global_load_ushort v153, v53, s[58:59] nt
	v_add_u32_e32 v53, 0x340000, v47
	global_load_ushort v154, v53, s[58:59] nt
	v_add_u32_e32 v53, 0x360000, v47
	global_load_ushort v155, v53, s[58:59] nt
	v_add_u32_e32 v53, 0x380000, v47
	global_load_ushort v156, v53, s[58:59] nt
	v_add_u32_e32 v53, 0x3a0000, v47
	global_load_ushort v157, v53, s[58:59] nt
	v_add_u32_e32 v53, 0x3c0000, v47
	global_load_ushort v158, v53, s[58:59] nt
	v_add_u32_e32 v53, 0x3e0000, v47
	global_load_ushort v159, v53, s[58:59] nt
	s_waitcnt lgkmcnt(0)
	s_load_dword s21, s[46:47], 0x200
	s_load_dword s22, s[46:47], 0x220
	s_load_dword s23, s[46:47], 0x240
	s_load_dword s24, s[46:47], 0x260
	s_load_dword s25, s[46:47], 0x280
	s_load_dword s26, s[46:47], 0x2a0
	s_load_dword s27, s[46:47], 0x2c0
	s_load_dword s37, s[46:47], 0x2e0
	s_load_dword s38, s[46:47], 0x300
	s_load_dword s39, s[46:47], 0x320
	s_load_dword s40, s[46:47], 0x340
	s_load_dword s41, s[46:47], 0x360
	s_load_dword s45, s[46:47], 0x380
	s_load_dword s48, s[46:47], 0x3a0
	s_load_dword s49, s[46:47], 0x3c0
	s_load_dword s32, s[46:47], 0x3e0
	v_cvt_pk_bf16_f32 v52, v10, v10
	buffer_store_short v52, v51, s[4:7], 0 offen sc1
	s_waitcnt vmcnt(32)
	v_lshlrev_b32_e32 v128, 16, v128
	v_fmac_f32_e32 v128, s64, v10
	v_mov_b32_e32 v10, v128
	v_cvt_pk_bf16_f32 v52, v10, v10
	s_mov_b32 s13, 0x20000
	buffer_store_short v52, v51, s[4:7], s13 offen sc1
	s_waitcnt vmcnt(32)
	v_lshlrev_b32_e32 v129, 16, v129
	v_fmac_f32_e32 v129, s65, v10
	v_mov_b32_e32 v10, v129
	v_cvt_pk_bf16_f32 v52, v10, v10
	s_mov_b32 s13, 0x40000
	buffer_store_short v52, v51, s[4:7], s13 offen sc1
	s_waitcnt vmcnt(32)
	v_lshlrev_b32_e32 v130, 16, v130
	v_fmac_f32_e32 v130, s66, v10
	v_mov_b32_e32 v10, v130
	v_cvt_pk_bf16_f32 v52, v10, v10
	s_mov_b32 s13, 0x60000
	buffer_store_short v52, v51, s[4:7], s13 offen sc1
	s_waitcnt vmcnt(32)
	v_lshlrev_b32_e32 v131, 16, v131
	v_fmac_f32_e32 v131, s67, v10
	v_mov_b32_e32 v10, v131
	v_cvt_pk_bf16_f32 v52, v10, v10
	s_mov_b32 s13, 0x80000
	buffer_store_short v52, v51, s[4:7], s13 offen sc1
	s_waitcnt vmcnt(32)
	v_lshlrev_b32_e32 v132, 16, v132
	v_fmac_f32_e32 v132, s68, v10
	v_mov_b32_e32 v10, v132
	v_cvt_pk_bf16_f32 v52, v10, v10
	s_mov_b32 s13, 0xa0000
	buffer_store_short v52, v51, s[4:7], s13 offen sc1
	s_waitcnt vmcnt(32)
	v_lshlrev_b32_e32 v133, 16, v133
	v_fmac_f32_e32 v133, s69, v10
	v_mov_b32_e32 v10, v133
	v_cvt_pk_bf16_f32 v52, v10, v10
	s_mov_b32 s13, 0xc0000
	buffer_store_short v52, v51, s[4:7], s13 offen sc1
	s_waitcnt vmcnt(32)
; __device__ __forceinline__ float bf2f(bf16 v) { return __uint_as_float(((unsigned)v) << 16); }
; __device__ __forceinline__ unsigned f2bfu(float f) { return (unsigned)__builtin_bit_cast(unsigned short, (__bf16)f); }
; __global__ void __launch_bounds__(NTHR, 2) k_main(Args a) {
;     ...
; #pragma unroll 1
;             for (int c0 = 0; c0 < 64; c0 += 8) {
;                 float st[8], dc[8];
; #pragma unroll
;                 for (int j = 0; j < 8; ++j) { const int bch = (b * 64 + c0 + j) * 8 + h; st[j] = bf2f(__builtin_nontemporal_load(&STATES[(size_t)bch * 8192 + pn])); dc[j] = CDEC[bch]; }
; #pragma unroll
;                 for (int j = 0; j < 8; ++j) { const int bch = (b * 64 + c0 + j) * 8 + h; __builtin_amdgcn_raw_buffer_store_b16((short)f2bfu(run), rsPV, (int)(((unsigned)bch * 8192u + (unsigned)pn) * 2u), 0, 16); run = dc[j] * run + st[j]; }
;             }
	v_lshlrev_b32_e32 v134, 16, v134
	v_fmac_f32_e32 v134, s70, v10
	v_mov_b32_e32 v10, v134
	v_cvt_pk_bf16_f32 v52, v10, v10
	s_mov_b32 s13, 0xe0000
	buffer_store_short v52, v51, s[4:7], s13 offen sc1
	s_waitcnt vmcnt(32)
	v_lshlrev_b32_e32 v135, 16, v135
	v_fmac_f32_e32 v135, s71, v10
	v_mov_b32_e32 v10, v135
	v_cvt_pk_bf16_f32 v52, v10, v10
	s_mov_b32 s13, 0x100000
	buffer_store_short v52, v51, s[4:7], s13 offen sc1
	s_waitcnt vmcnt(32)
	v_lshlrev_b32_e32 v136, 16, v136
	v_fmac_f32_e32 v136, s72, v10
	v_mov_b32_e32 v10, v136
	v_cvt_pk_bf16_f32 v52, v10, v10
	s_mov_b32 s13, 0x120000
	buffer_store_short v52, v51, s[4:7], s13 offen sc1
	s_waitcnt vmcnt(32)
	v_lshlrev_b32_e32 v137, 16, v137
	v_fmac_f32_e32 v137, s73, v10
	v_mov_b32_e32 v10, v137
	v_cvt_pk_bf16_f32 v52, v10, v10
	s_mov_b32 s13, 0x140000
	buffer_store_short v52, v51, s[4:7], s13 offen sc1
	s_waitcnt vmcnt(32)
	v_lshlrev_b32_e32 v138, 16, v138
	v_fmac_f32_e32 v138, s74, v10
	v_mov_b32_e32 v10, v138
	v_cvt_pk_bf16_f32 v52, v10, v10
	s_mov_b32 s13, 0x160000
	buffer_store_short v52, v51, s[4:7], s13 offen sc1
	s_waitcnt vmcnt(32)
	v_lshlrev_b32_e32 v139, 16, v139
	v_fmac_f32_e32 v139, s75, v10
	v_mov_b32_e32 v10, v139
	v_cvt_pk_bf16_f32 v52, v10, v10
	s_mov_b32 s13, 0x180000
	buffer_store_short v52, v51, s[4:7], s13 offen sc1
	s_waitcnt vmcnt(32)
	v_lshlrev_b32_e32 v140, 16, v140
	v_fmac_f32_e32 v140, s76, v10
	v_mov_b32_e32 v10, v140
	v_cvt_pk_bf16_f32 v52, v10, v10
	s_mov_b32 s13, 0x1a0000
	buffer_store_short v52, v51, s[4:7], s13 offen sc1
	s_waitcnt vmcnt(32)
	v_lshlrev_b32_e32 v141, 16, v141
	v_fmac_f32_e32 v141, s77, v10
	v_mov_b32_e32 v10, v141
	v_cvt_pk_bf16_f32 v52, v10, v10
	s_mov_b32 s13, 0x1c0000
	buffer_store_short v52, v51, s[4:7], s13 offen sc1
	s_waitcnt vmcnt(32)
	v_lshlrev_b32_e32 v142, 16, v142
	v_fmac_f32_e32 v142, s78, v10
	v_mov_b32_e32 v10, v142
	v_cvt_pk_bf16_f32 v52, v10, v10
	s_mov_b32 s13, 0x1e0000
	buffer_store_short v52, v51, s[4:7], s13 offen sc1
	s_waitcnt vmcnt(32)
	v_lshlrev_b32_e32 v143, 16, v143
	v_fmac_f32_e32 v143, s79, v10
	v_mov_b32_e32 v10, v143
	v_add_u32_e32 v53, 0x400000, v47
	global_load_ushort v128, v53, s[58:59] nt
	v_add_u32_e32 v53, 0x420000, v47
	global_load_ushort v129, v53, s[58:59] nt
	v_add_u32_e32 v53, 0x440000, v47
	global_load_ushort v130, v53, s[58:59] nt
	v_add_u32_e32 v53, 0x460000, v47
	global_load_ushort v131, v53, s[58:59] nt
	v_add_u32_e32 v53, 0x480000, v47
	global_load_ushort v132, v53, s[58:59] nt
	v_add_u32_e32 v53, 0x4a0000, v47
	global_load_ushort v133, v53, s[58:59] nt
	v_add_u32_e32 v53, 0x4c0000, v47
	global_load_ushort v134, v53, s[58:59] nt
	v_add_u32_e32 v53, 0x4e0000, v47
	global_load_ushort v135, v53, s[58:59] nt
	v_add_u32_e32 v53, 0x500000, v47
	global_load_ushort v136, v53, s[58:59] nt
	v_add_u32_e32 v53, 0x520000, v47
	global_load_ushort v137, v53, s[58:59] nt
	v_add_u32_e32 v53, 0x540000, v47
	global_load_ushort v138, v53, s[58:59] nt
	v_add_u32_e32 v53, 0x560000, v47
	global_load_ushort v139, v53, s[58:59] nt
	v_add_u32_e32 v53, 0x580000, v47
	global_load_ushort v140, v53, s[58:59] nt
	v_add_u32_e32 v53, 0x5a0000, v47
	global_load_ushort v141, v53, s[58:59] nt
	v_add_u32_e32 v53, 0x5c0000, v47
	global_load_ushort v142, v53, s[58:59] nt
	v_add_u32_e32 v53, 0x5e0000, v47
	global_load_ushort v143, v53, s[58:59] nt
	s_waitcnt lgkmcnt(0)
	s_load_dword s64, s[46:47], 0x400
	s_load_dword s65, s[46:47], 0x420
	s_load_dword s66, s[46:47], 0x440
	s_load_dword s67, s[46:47], 0x460
	s_load_dword s68, s[46:47], 0x480
	s_load_dword s69, s[46:47], 0x4a0
	s_load_dword s70, s[46:47], 0x4c0
	s_load_dword s71, s[46:47], 0x4e0
	s_load_dword s72, s[46:47], 0x500
	s_load_dword s73, s[46:47], 0x520
	s_load_dword s74, s[46:47], 0x540
	s_load_dword s75, s[46:47], 0x560
	s_load_dword s76, s[46:47], 0x580
	s_load_dword s77, s[46:47], 0x5a0
	s_load_dword s78, s[46:47], 0x5c0
	s_load_dword s79, s[46:47], 0x5e0
	v_cvt_pk_bf16_f32 v52, v10, v10
	s_mov_b32 s13, 0x200000
	buffer_store_short v52, v51, s[4:7], s13 offen sc1
	s_waitcnt vmcnt(48)
	v_lshlrev_b32_e32 v144, 16, v144
	v_fmac_f32_e32 v144, s21, v10
	v_mov_b32_e32 v10, v144
	v_cvt_pk_bf16_f32 v52, v10, v10
	s_mov_b32 s13, 0x220000
	buffer_store_short v52, v51, s[4:7], s13 offen sc1
	s_waitcnt vmcnt(48)
	v_lshlrev_b32_e32 v145, 16, v145
	v_fmac_f32_e32 v145, s22, v10
	v_mov_b32_e32 v10, v145
	v_cvt_pk_bf16_f32 v52, v10, v10
	s_mov_b32 s13, 0x240000
	buffer_store_short v52, v51, s[4:7], s13 offen sc1
	s_waitcnt vmcnt(48)
	v_lshlrev_b32_e32 v146, 16, v146
	v_fmac_f32_e32 v146, s23, v10
	v_mov_b32_e32 v10, v146
	v_cvt_pk_bf16_f32 v52, v10, v10
	s_mov_b32 s13, 0x260000
	buffer_store_short v52, v51, s[4:7], s13 offen sc1
	s_waitcnt vmcnt(48)
	v_lshlrev_b32_e32 v147, 16, v147
	v_fmac_f32_e32 v147, s24, v10
	v_mov_b32_e32 v10, v147
	v_cvt_pk_bf16_f32 v52, v10, v10
	s_mov_b32 s13, 0x280000
	buffer_store_short v52, v51, s[4:7], s13 offen sc1
	s_waitcnt vmcnt(48)
	v_lshlrev_b32_e32 v148, 16, v148
	v_fmac_f32_e32 v148, s25, v10
	v_mov_b32_e32 v10, v148
	v_cvt_pk_bf16_f32 v52, v10, v10
	s_mov_b32 s13, 0x2a0000
	buffer_store_short v52, v51, s[4:7], s13 offen sc1
	s_waitcnt vmcnt(48)
	v_lshlrev_b32_e32 v149, 16, v149
	v_fmac_f32_e32 v149, s26, v10
	v_mov_b32_e32 v10, v149
	v_cvt_pk_bf16_f32 v52, v10, v10
	s_mov_b32 s13, 0x2c0000
	buffer_store_short v52, v51, s[4:7], s13 offen sc1
	s_waitcnt vmcnt(48)
	v_lshlrev_b32_e32 v150, 16, v150
	v_fmac_f32_e32 v150, s27, v10
	v_mov_b32_e32 v10, v150
	v_cvt_pk_bf16_f32 v52, v10, v10
	s_mov_b32 s13, 0x2e0000
	buffer_store_short v52, v51, s[4:7], s13 offen sc1
	s_waitcnt vmcnt(48)
; __device__ __forceinline__ float bf2f(bf16 v) { return __uint_as_float(((unsigned)v) << 16); }
; __device__ __forceinline__ unsigned f2bfu(float f) { return (unsigned)__builtin_bit_cast(unsigned short, (__bf16)f); }
; __global__ void __launch_bounds__(NTHR, 2) k_main(Args a) {
;     ...
; #pragma unroll 1
;             for (int c0 = 0; c0 < 64; c0 += 8) {
;                 float st[8], dc[8];
; #pragma unroll
;                 for (int j = 0; j < 8; ++j) { const int bch = (b * 64 + c0 + j) * 8 + h; st[j] = bf2f(__builtin_nontemporal_load(&STATES[(size_t)bch * 8192 + pn])); dc[j] = CDEC[bch]; }
; #pragma unroll
;                 for (int j = 0; j < 8; ++j) { const int bch = (b * 64 + c0 + j) * 8 + h; __builtin_amdgcn_raw_buffer_store_b16((short)f2bfu(run), rsPV, (int)(((unsigned)bch * 8192u + (unsigned)pn) * 2u), 0, 16); run = dc[j] * run + st[j]; }
;             }
	v_lshlrev_b32_e32 v151, 16, v151
	v_fmac_f32_e32 v151, s37, v10
	v_mov_b32_e32 v10, v151
	v_cvt_pk_bf16_f32 v52, v10, v10
	s_mov_b32 s13, 0x300000
	buffer_store_short v52, v51, s[4:7], s13 offen sc1
	s_waitcnt vmcnt(48)
	v_lshlrev_b32_e32 v152, 16, v152
	v_fmac_f32_e32 v152, s38, v10
	v_mov_b32_e32 v10, v152
	v_cvt_pk_bf16_f32 v52, v10, v10
	s_mov_b32 s13, 0x320000
	buffer_store_short v52, v51, s[4:7], s13 offen sc1
	s_waitcnt vmcnt(48)
	v_lshlrev_b32_e32 v153, 16, v153
	v_fmac_f32_e32 v153, s39, v10
	v_mov_b32_e32 v10, v153
	v_cvt_pk_bf16_f32 v52, v10, v10
	s_mov_b32 s13, 0x340000
	buffer_store_short v52, v51, s[4:7], s13 offen sc1
	s_waitcnt vmcnt(48)
	v_lshlrev_b32_e32 v154, 16, v154
	v_fmac_f32_e32 v154, s40, v10
	v_mov_b32_e32 v10, v154
	v_cvt_pk_bf16_f32 v52, v10, v10
	s_mov_b32 s13, 0x360000
	buffer_store_short v52, v51, s[4:7], s13 offen sc1
	s_waitcnt vmcnt(48)
	v_lshlrev_b32_e32 v155, 16, v155
	v_fmac_f32_e32 v155, s41, v10
	v_mov_b32_e32 v10, v155
	v_cvt_pk_bf16_f32 v52, v10, v10
	s_mov_b32 s13, 0x380000
	buffer_store_short v52, v51, s[4:7], s13 offen sc1
	s_waitcnt vmcnt(48)
	v_lshlrev_b32_e32 v156, 16, v156
	v_fmac_f32_e32 v156, s45, v10
	v_mov_b32_e32 v10, v156
	v_cvt_pk_bf16_f32 v52, v10, v10
	s_mov_b32 s13, 0x3a0000
	buffer_store_short v52, v51, s[4:7], s13 offen sc1
	s_waitcnt vmcnt(48)
	v_lshlrev_b32_e32 v157, 16, v157
	v_fmac_f32_e32 v157, s48, v10
	v_mov_b32_e32 v10, v157
	v_cvt_pk_bf16_f32 v52, v10, v10
	s_mov_b32 s13, 0x3c0000
	buffer_store_short v52, v51, s[4:7], s13 offen sc1
	s_waitcnt vmcnt(48)
	v_lshlrev_b32_e32 v158, 16, v158
	v_fmac_f32_e32 v158, s49, v10
	v_mov_b32_e32 v10, v158
	v_cvt_pk_bf16_f32 v52, v10, v10
	s_mov_b32 s13, 0x3e0000
	buffer_store_short v52, v51, s[4:7], s13 offen sc1
	s_waitcnt vmcnt(48)
	v_lshlrev_b32_e32 v159, 16, v159
	v_fmac_f32_e32 v159, s32, v10
	v_mov_b32_e32 v10, v159
	v_add_u32_e32 v53, 0x600000, v47
	global_load_ushort v144, v53, s[58:59] nt
	v_add_u32_e32 v53, 0x620000, v47
	global_load_ushort v145, v53, s[58:59] nt
	v_add_u32_e32 v53, 0x640000, v47
	global_load_ushort v146, v53, s[58:59] nt
	v_add_u32_e32 v53, 0x660000, v47
	global_load_ushort v147, v53, s[58:59] nt
	v_add_u32_e32 v53, 0x680000, v47
	global_load_ushort v148, v53, s[58:59] nt
	v_add_u32_e32 v53, 0x6a0000, v47
	global_load_ushort v149, v53, s[58:59] nt
	v_add_u32_e32 v53, 0x6c0000, v47
	global_load_ushort v150, v53, s[58:59] nt
	v_add_u32_e32 v53, 0x6e0000, v47
	global_load_ushort v151, v53, s[58:59] nt
	v_add_u32_e32 v53, 0x700000, v47
	global_load_ushort v152, v53, s[58:59] nt
	v_add_u32_e32 v53, 0x720000, v47
	global_load_ushort v153, v53, s[58:59] nt
	v_add_u32_e32 v53, 0x740000, v47
	global_load_ushort v154, v53, s[58:59] nt
	v_add_u32_e32 v53, 0x760000, v47
	global_load_ushort v155, v53, s[58:59] nt
	v_add_u32_e32 v53, 0x780000, v47
	global_load_ushort v156, v53, s[58:59] nt
	v_add_u32_e32 v53, 0x7a0000, v47
	global_load_ushort v157, v53, s[58:59] nt
	v_add_u32_e32 v53, 0x7c0000, v47
	global_load_ushort v158, v53, s[58:59] nt
	v_add_u32_e32 v53, 0x7e0000, v47
	global_load_ushort v159, v53, s[58:59] nt
	s_waitcnt lgkmcnt(0)
	s_load_dword s21, s[46:47], 0x600
	s_load_dword s22, s[46:47], 0x620
	s_load_dword s23, s[46:47], 0x640
	s_load_dword s24, s[46:47], 0x660
	s_load_dword s25, s[46:47], 0x680
	s_load_dword s26, s[46:47], 0x6a0
	s_load_dword s27, s[46:47], 0x6c0
	s_load_dword s37, s[46:47], 0x6e0
	s_load_dword s38, s[46:47], 0x700
	s_load_dword s39, s[46:47], 0x720
	s_load_dword s40, s[46:47], 0x740
	s_load_dword s41, s[46:47], 0x760
	s_load_dword s45, s[46:47], 0x780
	s_load_dword s48, s[46:47], 0x7a0
	s_load_dword s49, s[46:47], 0x7c0
	s_load_dword s32, s[46:47], 0x7e0
	v_cvt_pk_bf16_f32 v52, v10, v10
	s_mov_b32 s13, 0x400000
	buffer_store_short v52, v51, s[4:7], s13 offen sc1
	s_waitcnt vmcnt(48)
	v_lshlrev_b32_e32 v128, 16, v128
	v_fmac_f32_e32 v128, s64, v10
	v_mov_b32_e32 v10, v128
	v_cvt_pk_bf16_f32 v52, v10, v10
	s_mov_b32 s13, 0x420000
	buffer_store_short v52, v51, s[4:7], s13 offen sc1
	s_waitcnt vmcnt(48)
	v_lshlrev_b32_e32 v129, 16, v129
	v_fmac_f32_e32 v129, s65, v10
	v_mov_b32_e32 v10, v129
	v_cvt_pk_bf16_f32 v52, v10, v10
	s_mov_b32 s13, 0x440000
	buffer_store_short v52, v51, s[4:7], s13 offen sc1
	s_waitcnt vmcnt(48)
	v_lshlrev_b32_e32 v130, 16, v130
	v_fmac_f32_e32 v130, s66, v10
	v_mov_b32_e32 v10, v130
	v_cvt_pk_bf16_f32 v52, v10, v10
	s_mov_b32 s13, 0x460000
	buffer_store_short v52, v51, s[4:7], s13 offen sc1
	s_waitcnt vmcnt(48)
	v_lshlrev_b32_e32 v131, 16, v131
	v_fmac_f32_e32 v131, s67, v10
	v_mov_b32_e32 v10, v131
	v_cvt_pk_bf16_f32 v52, v10, v10
	s_mov_b32 s13, 0x480000
	buffer_store_short v52, v51, s[4:7], s13 offen sc1
	s_waitcnt vmcnt(48)
	v_lshlrev_b32_e32 v132, 16, v132
	v_fmac_f32_e32 v132, s68, v10
	v_mov_b32_e32 v10, v132
	v_cvt_pk_bf16_f32 v52, v10, v10
	s_mov_b32 s13, 0x4a0000
	buffer_store_short v52, v51, s[4:7], s13 offen sc1
	s_waitcnt vmcnt(48)
	v_lshlrev_b32_e32 v133, 16, v133
	v_fmac_f32_e32 v133, s69, v10
	v_mov_b32_e32 v10, v133
	v_cvt_pk_bf16_f32 v52, v10, v10
	s_mov_b32 s13, 0x4c0000
	buffer_store_short v52, v51, s[4:7], s13 offen sc1
	s_waitcnt vmcnt(48)
	v_lshlrev_b32_e32 v134, 16, v134
	v_fmac_f32_e32 v134, s70, v10
	v_mov_b32_e32 v10, v134
	v_cvt_pk_bf16_f32 v52, v10, v10
	s_mov_b32 s13, 0x4e0000
	buffer_store_short v52, v51, s[4:7], s13 offen sc1
	s_waitcnt vmcnt(48)
	v_lshlrev_b32_e32 v135, 16, v135
	v_fmac_f32_e32 v135, s71, v10
	v_mov_b32_e32 v10, v135
	v_cvt_pk_bf16_f32 v52, v10, v10
	s_mov_b32 s13, 0x500000
	buffer_store_short v52, v51, s[4:7], s13 offen sc1
	s_waitcnt vmcnt(48)
; __device__ __forceinline__ float bf2f(bf16 v) { return __uint_as_float(((unsigned)v) << 16); }
; __device__ __forceinline__ unsigned f2bfu(float f) { return (unsigned)__builtin_bit_cast(unsigned short, (__bf16)f); }
; __global__ void __launch_bounds__(NTHR, 2) k_main(Args a) {
;     ...
; #pragma unroll 1
;             for (int c0 = 0; c0 < 64; c0 += 8) {
;                 float st[8], dc[8];
; #pragma unroll
;                 for (int j = 0; j < 8; ++j) { const int bch = (b * 64 + c0 + j) * 8 + h; st[j] = bf2f(__builtin_nontemporal_load(&STATES[(size_t)bch * 8192 + pn])); dc[j] = CDEC[bch]; }
; #pragma unroll
;                 for (int j = 0; j < 8; ++j) { const int bch = (b * 64 + c0 + j) * 8 + h; __builtin_amdgcn_raw_buffer_store_b16((short)f2bfu(run), rsPV, (int)(((unsigned)bch * 8192u + (unsigned)pn) * 2u), 0, 16); run = dc[j] * run + st[j]; }
;             }
	v_lshlrev_b32_e32 v136, 16, v136
	v_fmac_f32_e32 v136, s72, v10
	v_mov_b32_e32 v10, v136
	v_cvt_pk_bf16_f32 v52, v10, v10
	s_mov_b32 s13, 0x520000
	buffer_store_short v52, v51, s[4:7], s13 offen sc1
	s_waitcnt vmcnt(48)
	v_lshlrev_b32_e32 v137, 16, v137
	v_fmac_f32_e32 v137, s73, v10
	v_mov_b32_e32 v10, v137
	v_cvt_pk_bf16_f32 v52, v10, v10
	s_mov_b32 s13, 0x540000
	buffer_store_short v52, v51, s[4:7], s13 offen sc1
	s_waitcnt vmcnt(48)
	v_lshlrev_b32_e32 v138, 16, v138
	v_fmac_f32_e32 v138, s74, v10
	v_mov_b32_e32 v10, v138
	v_cvt_pk_bf16_f32 v52, v10, v10
	s_mov_b32 s13, 0x560000
	buffer_store_short v52, v51, s[4:7], s13 offen sc1
	s_waitcnt vmcnt(48)
	v_lshlrev_b32_e32 v139, 16, v139
	v_fmac_f32_e32 v139, s75, v10
	v_mov_b32_e32 v10, v139
	v_cvt_pk_bf16_f32 v52, v10, v10
	s_mov_b32 s13, 0x580000
	buffer_store_short v52, v51, s[4:7], s13 offen sc1
	s_waitcnt vmcnt(48)
	v_lshlrev_b32_e32 v140, 16, v140
	v_fmac_f32_e32 v140, s76, v10
	v_mov_b32_e32 v10, v140
	v_cvt_pk_bf16_f32 v52, v10, v10
	s_mov_b32 s13, 0x5a0000
	buffer_store_short v52, v51, s[4:7], s13 offen sc1
	s_waitcnt vmcnt(48)
	v_lshlrev_b32_e32 v141, 16, v141
	v_fmac_f32_e32 v141, s77, v10
	v_mov_b32_e32 v10, v141
	v_cvt_pk_bf16_f32 v52, v10, v10
	s_mov_b32 s13, 0x5c0000
	buffer_store_short v52, v51, s[4:7], s13 offen sc1
	s_waitcnt vmcnt(48)
	v_lshlrev_b32_e32 v142, 16, v142
	v_fmac_f32_e32 v142, s78, v10
	v_mov_b32_e32 v10, v142
	v_cvt_pk_bf16_f32 v52, v10, v10
	s_mov_b32 s13, 0x5e0000
	buffer_store_short v52, v51, s[4:7], s13 offen sc1
	s_waitcnt vmcnt(48)
	v_lshlrev_b32_e32 v143, 16, v143
	v_fmac_f32_e32 v143, s79, v10
	v_mov_b32_e32 v10, v143
	s_waitcnt lgkmcnt(0)
	v_cvt_pk_bf16_f32 v52, v10, v10
	s_mov_b32 s13, 0x600000
	buffer_store_short v52, v51, s[4:7], s13 offen sc1
	s_waitcnt vmcnt(32)
	v_lshlrev_b32_e32 v144, 16, v144
	v_fmac_f32_e32 v144, s21, v10
	v_mov_b32_e32 v10, v144
	v_cvt_pk_bf16_f32 v52, v10, v10
	s_mov_b32 s13, 0x620000
	buffer_store_short v52, v51, s[4:7], s13 offen sc1
	s_waitcnt vmcnt(32)
	v_lshlrev_b32_e32 v145, 16, v145
	v_fmac_f32_e32 v145, s22, v10
	v_mov_b32_e32 v10, v145
	v_cvt_pk_bf16_f32 v52, v10, v10
	s_mov_b32 s13, 0x640000
	buffer_store_short v52, v51, s[4:7], s13 offen sc1
	s_waitcnt vmcnt(32)
	v_lshlrev_b32_e32 v146, 16, v146
	v_fmac_f32_e32 v146, s23, v10
	v_mov_b32_e32 v10, v146
	v_cvt_pk_bf16_f32 v52, v10, v10
	s_mov_b32 s13, 0x660000
	buffer_store_short v52, v51, s[4:7], s13 offen sc1
	s_waitcnt vmcnt(32)
	v_lshlrev_b32_e32 v147, 16, v147
	v_fmac_f32_e32 v147, s24, v10
	v_mov_b32_e32 v10, v147
	v_cvt_pk_bf16_f32 v52, v10, v10
	s_mov_b32 s13, 0x680000
	buffer_store_short v52, v51, s[4:7], s13 offen sc1
	s_waitcnt vmcnt(32)
	v_lshlrev_b32_e32 v148, 16, v148
	v_fmac_f32_e32 v148, s25, v10
	v_mov_b32_e32 v10, v148
	v_cvt_pk_bf16_f32 v52, v10, v10
	s_mov_b32 s13, 0x6a0000
	buffer_store_short v52, v51, s[4:7], s13 offen sc1
	s_waitcnt vmcnt(32)
	v_lshlrev_b32_e32 v149, 16, v149
	v_fmac_f32_e32 v149, s26, v10
	v_mov_b32_e32 v10, v149
	v_cvt_pk_bf16_f32 v52, v10, v10
	s_mov_b32 s13, 0x6c0000
	buffer_store_short v52, v51, s[4:7], s13 offen sc1
	s_waitcnt vmcnt(32)
	v_lshlrev_b32_e32 v150, 16, v150
	v_fmac_f32_e32 v150, s27, v10
	v_mov_b32_e32 v10, v150
	v_cvt_pk_bf16_f32 v52, v10, v10
	s_mov_b32 s13, 0x6e0000
	buffer_store_short v52, v51, s[4:7], s13 offen sc1
	s_waitcnt vmcnt(32)
	v_lshlrev_b32_e32 v151, 16, v151
	v_fmac_f32_e32 v151, s37, v10
	v_mov_b32_e32 v10, v151
	v_cvt_pk_bf16_f32 v52, v10, v10
	s_mov_b32 s13, 0x700000
	buffer_store_short v52, v51, s[4:7], s13 offen sc1
	s_waitcnt vmcnt(32)
	v_lshlrev_b32_e32 v152, 16, v152
	v_fmac_f32_e32 v152, s38, v10
	v_mov_b32_e32 v10, v152
	v_cvt_pk_bf16_f32 v52, v10, v10
	s_mov_b32 s13, 0x720000
	buffer_store_short v52, v51, s[4:7], s13 offen sc1
	s_waitcnt vmcnt(32)
	v_lshlrev_b32_e32 v153, 16, v153
	v_fmac_f32_e32 v153, s39, v10
	v_mov_b32_e32 v10, v153
	v_cvt_pk_bf16_f32 v52, v10, v10
	s_mov_b32 s13, 0x740000
	buffer_store_short v52, v51, s[4:7], s13 offen sc1
	s_waitcnt vmcnt(32)
	v_lshlrev_b32_e32 v154, 16, v154
	v_fmac_f32_e32 v154, s40, v10
	v_mov_b32_e32 v10, v154
	v_cvt_pk_bf16_f32 v52, v10, v10
	s_mov_b32 s13, 0x760000
	buffer_store_short v52, v51, s[4:7], s13 offen sc1
	s_waitcnt vmcnt(32)
	v_lshlrev_b32_e32 v155, 16, v155
	v_fmac_f32_e32 v155, s41, v10
	v_mov_b32_e32 v10, v155
	v_cvt_pk_bf16_f32 v52, v10, v10
	s_mov_b32 s13, 0x780000
	buffer_store_short v52, v51, s[4:7], s13 offen sc1
	s_waitcnt vmcnt(32)
	v_lshlrev_b32_e32 v156, 16, v156
	v_fmac_f32_e32 v156, s45, v10
	v_mov_b32_e32 v10, v156
	v_cvt_pk_bf16_f32 v52, v10, v10
	s_mov_b32 s13, 0x7a0000
	buffer_store_short v52, v51, s[4:7], s13 offen sc1
	s_waitcnt vmcnt(32)
	v_lshlrev_b32_e32 v157, 16, v157
	v_fmac_f32_e32 v157, s48, v10
	v_mov_b32_e32 v10, v157
	v_cvt_pk_bf16_f32 v52, v10, v10
	s_mov_b32 s13, 0x7c0000
	buffer_store_short v52, v51, s[4:7], s13 offen sc1
	s_waitcnt vmcnt(32)
	v_lshlrev_b32_e32 v158, 16, v158
	v_fmac_f32_e32 v158, s49, v10
	v_mov_b32_e32 v10, v158
	v_cvt_pk_bf16_f32 v52, v10, v10
	s_mov_b32 s13, 0x7e0000
	buffer_store_short v52, v51, s[4:7], s13 offen sc1
	s_waitcnt vmcnt(32)
	v_lshlrev_b32_e32 v159, 16, v159
	v_fmac_f32_e32 v159, s32, v10
	v_mov_b32_e32 v10, v159
	v_add_u32_e32 v8, s56, v8
	v_cmp_lt_i32_e32 vcc, s11, v8
	s_or_b64 s[8:9], vcc, s[8:9]
	v_add_u32_e32 v9, s3, v9
	s_andn2_b64 exec, exec, s[8:9]
	s_cbranch_execnz .LBB0_377

; __device__ __forceinline__ void xn2_rows(const bf16* __restrict__ hb, const float* __restrict__ g, bf16* __restrict__ outp, unsigned char* __restrict__ xq, float* __restrict__ xs, int gwave, int nwaves, int lane, int rend) {
;     ...
;     for (int row = gwave; row < rend; row += nwaves) {
;         const v4u* xb = (const v4u*)(hb + (size_t)row * D) + lane;
;         float v[2][8]; float ss = 0.f;
; #pragma unroll
;         for (int j = 0; j < 2; ++j) { const v4u w = xb[64 * j]; const unsigned ww[4] = {w.x, w.y, w.z, w.w};
; #pragma unroll
;             for (int e = 0; e < 4; ++e) { v[j][2 * e] = __uint_as_float(ww[e] << 16); v[j][2 * e + 1] = __uint_as_float(ww[e] & 0xffff0000u); ss += v[j][2 * e] * v[j][2 * e] + v[j][2 * e + 1] * v[j][2 * e + 1]; } }
;         ss = wave_sum(ss);
;         const float r = rsqrtf(ss * (1.f / D) + EPS);
;         float y[2][8]; float mx = 0.f;
; #pragma unroll
;         for (int j = 0; j < 2; ++j) { const float4 g0 = ((const float4*)g)[2 * lane + 128 * j], g1 = ((const float4*)g)[2 * lane + 128 * j + 1]; const float gg[8] = {g0.x, g0.y, g0.z, g0.w, g1.x, g1.y, g1.z, g1.w};
; #pragma unroll
;             for (int e = 0; e < 8; ++e) { y[j][e] = v[j][e] * r * gg[e]; mx = fmaxf(mx, fabsf(y[j][e])); }
;             v4u ow; ow.x = pk2(y[j][0], y[j][1]); ow.y = pk2(y[j][2], y[j][3]); ow.z = pk2(y[j][4], y[j][5]); ow.w = pk2(y[j][6], y[j][7]);
;             __builtin_amdgcn_raw_buffer_store_b128(ow, rsO, (int)(((unsigned)row * D + 8u * (unsigned)lane + 512u * j) * 2u), 0, 16); }
;         mx = wave_max_dpp(mx);
;         const float sc = mx > 0.f ? mx * (1.f / 119.f) : 1.f, inv = 1.f / sc;
.LBB0_564:
	s_or_b64 exec, exec, s[10:11]
	s_andn2_b64 vcc, exec, s[20:21]
	s_barrier
	s_cbranch_vccnz .LBB0_569
	s_nop 0
	s_nop 0
	s_nop 0
	s_nop 0
	s_nop 0
	s_nop 0
	s_nop 0
	s_nop 0
	s_nop 0
	s_nop 0
	s_nop 0
	s_nop 0
	s_nop 0
	s_nop 0
	s_nop 0
	global_load_dwordx4 v[2:5], v[20:21], off offset:16
	global_load_dwordx4 v[6:9], v[20:21], off
	global_load_dwordx4 v[10:13], v[20:21], off offset:2064
	global_load_dwordx4 v[14:17], v[20:21], off offset:2048
	s_lshl_b32 s10, s42, 6
	s_lshl_b32 s11, s43, 8
	s_add_i32 s24, s10, s11
	s_add_i32 s24, s24, s95
	s_ashr_i32 s25, s24, 31
	s_lshl_b64 s[10:11], s[24:25], 2
	s_lshl_b32 s98, s95, 2
	v_lshl_add_u32 v33, s24, 9, v1
	s_lshl_b64 s[24:25], s[24:25], 11
	v_mov_b32_e32 v27, s25
	v_or_b32_e32 v26, s24, v18
	v_lshl_add_u64 v[148:149], s[90:91], 0, v[26:27]
	s_mov_b32 s24, 0xa400000
	s_mov_b32 s25, 0
	s_nop 0
	v_lshl_add_u64 v[148:149], v[148:149], 0, s[24:25]
	v_lshl_add_u64 v[150:151], v[148:149], 0, s[22:23]
	global_load_dwordx4 v[84:87], v[148:149], off
	global_load_dwordx4 v[88:91], v[148:149], off offset:1024
	global_load_dwordx4 v[92:95], v[150:151], off
	global_load_dwordx4 v[96:99], v[150:151], off offset:1024
	s_mov_b32 s46, 0x4b400008
	s_mov_b32 s47, 0x4b400008
	s_mov_b32 s48, 0x0c0c0400
	s_mov_b32 s49, 0x05040100
	s_mov_b32 s45, 0x0f0f0f0f
	s_mov_b32 s100, 0x8000
	s_mov_b32 s101, 0
	s_mov_b32 s32, 0
	v_mov_b32_e32 v55, 0
	v_mov_b32_e32 v61, 0
	v_mov_b32_e32 v210, v26
	v_mov_b32_e32 v211, v33
	s_waitcnt vmcnt(0)
